# last phase: f32 result stores with sc0 nt instead of nt
# speedup vs baseline: 1.0028x; 1.0028x over previous
.LBB0_1746:
	s_andn2_b64 vcc, exec, s[8:9]
	s_cbranch_vccnz .LBB0_1748
	v_lshl_add_u32 v150, s26, 8, v1
	v_lshl_or_b32 v148, s51, 8, v153
	v_ashrrev_i32_e32 v151, 31, v150
	v_ashrrev_i32_e32 v149, 31, v148
	v_lshlrev_b64 v[146:147], 10, v[150:151]
	v_lshl_add_u64 v[146:147], v[146:147], 0, v[148:149]
	v_lshlrev_b64 v[162:163], 1, v[146:147]
	v_lshl_add_u64 v[158:159], s[78:79], 0, v[162:163]
	global_load_dwordx4 v[158:161], v[158:159], off
	v_lshl_add_u64 v[164:165], v[146:147], 2, s[70:71]
	v_or_b32_e32 v162, 0x100, v162
	v_lshl_add_u64 v[162:163], s[78:79], 0, v[162:163]
	s_waitcnt vmcnt(0)
	v_lshlrev_b32_e32 v168, 16, v158
	v_and_b32_e32 v169, 0xffff0000, v158
	v_lshlrev_b32_e32 v158, 16, v159
	v_and_b32_e32 v159, 0xffff0000, v159
	v_lshlrev_b32_e32 v166, 16, v160
	v_and_b32_e32 v167, 0xffff0000, v160
	v_lshlrev_b32_e32 v160, 16, v161
	v_and_b32_e32 v161, 0xffff0000, v161
	v_pk_add_f32 v[128:129], v[128:129], v[158:159]
	v_pk_add_f32 v[126:127], v[126:127], v[168:169]
	v_pk_add_f32 v[124:125], v[124:125], v[160:161]
	v_pk_add_f32 v[122:123], v[122:123], v[166:167]
	global_store_dwordx4 v[164:165], v[126:129], off sc0 nt
	global_store_dwordx4 v[164:165], v[122:125], off offset:16 sc0 nt
	global_load_dwordx4 v[122:125], v[162:163], off
	v_or_b32_e32 v126, 16, v150
	v_ashrrev_i32_e32 v127, 31, v126
	v_lshlrev_b64 v[126:127], 10, v[126:127]
	v_lshl_add_u64 v[126:127], v[126:127], 0, v[148:149]
	v_lshlrev_b64 v[128:129], 1, v[126:127]
	v_lshl_add_u64 v[158:159], s[78:79], 0, v[128:129]
	v_or_b32_e32 v128, 0x100, v128
	s_waitcnt vmcnt(0)
	v_lshlrev_b32_e32 v162, 16, v122
	v_and_b32_e32 v163, 0xffff0000, v122
	v_lshlrev_b32_e32 v122, 16, v123
	v_and_b32_e32 v123, 0xffff0000, v123
	v_lshlrev_b32_e32 v160, 16, v124
	v_and_b32_e32 v161, 0xffff0000, v124
	v_lshlrev_b32_e32 v124, 16, v125
	v_and_b32_e32 v125, 0xffff0000, v125
	v_pk_add_f32 v[120:121], v[120:121], v[122:123]
	v_pk_add_f32 v[118:119], v[118:119], v[162:163]
	v_pk_add_f32 v[116:117], v[116:117], v[124:125]
	v_pk_add_f32 v[114:115], v[114:115], v[160:161]
	global_store_dwordx4 v[164:165], v[118:121], off offset:512 sc0 nt
	global_store_dwordx4 v[164:165], v[114:117], off offset:528 sc0 nt
	global_load_dwordx4 v[114:117], v[158:159], off
	v_lshl_add_u64 v[118:119], v[126:127], 2, s[70:71]
	v_lshl_add_u64 v[120:121], s[78:79], 0, v[128:129]
	s_waitcnt vmcnt(0)
	v_lshlrev_b32_e32 v124, 16, v114
	v_and_b32_e32 v125, 0xffff0000, v114
	v_lshlrev_b32_e32 v114, 16, v115
	v_and_b32_e32 v115, 0xffff0000, v115
	v_lshlrev_b32_e32 v122, 16, v116
	v_and_b32_e32 v123, 0xffff0000, v116
	v_lshlrev_b32_e32 v116, 16, v117
	v_and_b32_e32 v117, 0xffff0000, v117
	v_pk_add_f32 v[112:113], v[112:113], v[114:115]
	v_pk_add_f32 v[110:111], v[110:111], v[124:125]
	v_pk_add_f32 v[108:109], v[108:109], v[116:117]
	v_pk_add_f32 v[106:107], v[106:107], v[122:123]
	global_store_dwordx4 v[118:119], v[110:113], off sc0 nt
	global_store_dwordx4 v[118:119], v[106:109], off offset:16 sc0 nt
	global_load_dwordx4 v[106:109], v[120:121], off
	v_or_b32_e32 v110, 32, v150
	v_ashrrev_i32_e32 v111, 31, v110
	v_lshlrev_b64 v[110:111], 10, v[110:111]
	v_lshl_add_u64 v[110:111], v[110:111], 0, v[148:149]
	v_lshlrev_b64 v[112:113], 1, v[110:111]
	v_lshl_add_u64 v[114:115], s[78:79], 0, v[112:113]
	v_or_b32_e32 v112, 0x100, v112
	s_waitcnt vmcnt(0)
	v_lshlrev_b32_e32 v120, 16, v106
	v_and_b32_e32 v121, 0xffff0000, v106
	v_lshlrev_b32_e32 v106, 16, v107
	v_and_b32_e32 v107, 0xffff0000, v107
	v_lshlrev_b32_e32 v116, 16, v108
	v_and_b32_e32 v117, 0xffff0000, v108
	v_lshlrev_b32_e32 v108, 16, v109
	v_and_b32_e32 v109, 0xffff0000, v109
	v_pk_add_f32 v[104:105], v[104:105], v[106:107]
	v_pk_add_f32 v[102:103], v[102:103], v[120:121]
	v_pk_add_f32 v[100:101], v[100:101], v[108:109]
	v_pk_add_f32 v[98:99], v[98:99], v[116:117]
	global_store_dwordx4 v[118:119], v[102:105], off offset:512 sc0 nt
	global_store_dwordx4 v[118:119], v[98:101], off offset:528 sc0 nt
	global_load_dwordx4 v[98:101], v[114:115], off
	v_lshl_add_u64 v[102:103], v[110:111], 2, s[70:71]
	v_lshl_add_u64 v[104:105], s[78:79], 0, v[112:113]
	s_waitcnt vmcnt(0)
	v_lshlrev_b32_e32 v108, 16, v98
	v_and_b32_e32 v109, 0xffff0000, v98
	v_lshlrev_b32_e32 v98, 16, v99
	v_and_b32_e32 v99, 0xffff0000, v99
	v_lshlrev_b32_e32 v106, 16, v100
	v_and_b32_e32 v107, 0xffff0000, v100
	v_lshlrev_b32_e32 v100, 16, v101
	v_and_b32_e32 v101, 0xffff0000, v101
	v_pk_add_f32 v[96:97], v[96:97], v[98:99]
	v_pk_add_f32 v[94:95], v[94:95], v[108:109]
	v_pk_add_f32 v[92:93], v[92:93], v[100:101]
	v_pk_add_f32 v[90:91], v[90:91], v[106:107]
	global_store_dwordx4 v[102:103], v[94:97], off sc0 nt
	global_store_dwordx4 v[102:103], v[90:93], off offset:16 sc0 nt
	global_load_dwordx4 v[90:93], v[104:105], off
	v_or_b32_e32 v94, 48, v150
	v_ashrrev_i32_e32 v95, 31, v94
	v_lshlrev_b64 v[94:95], 10, v[94:95]
	v_lshl_add_u64 v[94:95], v[94:95], 0, v[148:149]
	v_lshlrev_b64 v[96:97], 1, v[94:95]
	v_lshl_add_u64 v[98:99], s[78:79], 0, v[96:97]
	v_or_b32_e32 v96, 0x100, v96
	s_waitcnt vmcnt(0)
	v_lshlrev_b32_e32 v104, 16, v90
	v_and_b32_e32 v105, 0xffff0000, v90
	v_lshlrev_b32_e32 v90, 16, v91
	v_and_b32_e32 v91, 0xffff0000, v91
	v_lshlrev_b32_e32 v100, 16, v92
	v_and_b32_e32 v101, 0xffff0000, v92
	v_lshlrev_b32_e32 v92, 16, v93
	v_and_b32_e32 v93, 0xffff0000, v93
	v_pk_add_f32 v[88:89], v[88:89], v[90:91]
	v_pk_add_f32 v[86:87], v[86:87], v[104:105]
	v_pk_add_f32 v[84:85], v[84:85], v[92:93]
	v_pk_add_f32 v[82:83], v[82:83], v[100:101]
	global_store_dwordx4 v[102:103], v[86:89], off offset:512 sc0 nt
	global_store_dwordx4 v[102:103], v[82:85], off offset:528 sc0 nt
	global_load_dwordx4 v[82:85], v[98:99], off
	v_lshl_add_u64 v[86:87], v[94:95], 2, s[70:71]
	v_lshl_add_u64 v[88:89], s[78:79], 0, v[96:97]
	s_waitcnt vmcnt(0)
	v_lshlrev_b32_e32 v92, 16, v82
	v_and_b32_e32 v93, 0xffff0000, v82
	v_lshlrev_b32_e32 v82, 16, v83
	v_and_b32_e32 v83, 0xffff0000, v83
	v_lshlrev_b32_e32 v90, 16, v84
	v_and_b32_e32 v91, 0xffff0000, v84
	v_lshlrev_b32_e32 v84, 16, v85
	v_and_b32_e32 v85, 0xffff0000, v85
	v_pk_add_f32 v[80:81], v[80:81], v[82:83]
	v_pk_add_f32 v[78:79], v[78:79], v[92:93]
	v_pk_add_f32 v[76:77], v[76:77], v[84:85]
	v_pk_add_f32 v[74:75], v[74:75], v[90:91]
	global_store_dwordx4 v[86:87], v[78:81], off sc0 nt
	global_store_dwordx4 v[86:87], v[74:77], off offset:16 sc0 nt
	global_load_dwordx4 v[74:77], v[88:89], off
	v_lshl_add_u64 v[78:79], v[146:147], 0, s[10:11]
	v_lshlrev_b64 v[80:81], 1, v[78:79]
	v_lshl_add_u64 v[82:83], s[78:79], 0, v[80:81]
	v_or_b32_e32 v80, 0x100, v80
	s_waitcnt vmcnt(0)
	v_lshlrev_b32_e32 v88, 16, v74
	v_and_b32_e32 v89, 0xffff0000, v74
	v_lshlrev_b32_e32 v74, 16, v75
	v_and_b32_e32 v75, 0xffff0000, v75
	v_lshlrev_b32_e32 v84, 16, v76
	v_and_b32_e32 v85, 0xffff0000, v76
	v_lshlrev_b32_e32 v76, 16, v77
	v_and_b32_e32 v77, 0xffff0000, v77
	v_pk_add_f32 v[72:73], v[72:73], v[74:75]
	v_pk_add_f32 v[70:71], v[70:71], v[88:89]
	v_pk_add_f32 v[68:69], v[68:69], v[76:77]
	v_pk_add_f32 v[66:67], v[66:67], v[84:85]
	global_store_dwordx4 v[86:87], v[70:73], off offset:512 sc0 nt
	global_store_dwordx4 v[86:87], v[66:69], off offset:528 sc0 nt
	global_load_dwordx4 v[66:69], v[82:83], off
	v_lshl_add_u64 v[70:71], v[78:79], 2, s[70:71]
	v_lshl_add_u64 v[72:73], s[78:79], 0, v[80:81]
	s_waitcnt vmcnt(0)
	v_lshlrev_b32_e32 v76, 16, v66
	v_and_b32_e32 v77, 0xffff0000, v66
	v_lshlrev_b32_e32 v66, 16, v67
	v_and_b32_e32 v67, 0xffff0000, v67
	v_lshlrev_b32_e32 v74, 16, v68
	v_and_b32_e32 v75, 0xffff0000, v68
	v_lshlrev_b32_e32 v68, 16, v69
	v_and_b32_e32 v69, 0xffff0000, v69
	v_pk_add_f32 v[64:65], v[64:65], v[66:67]
	v_pk_add_f32 v[62:63], v[62:63], v[76:77]
	v_pk_add_f32 v[60:61], v[60:61], v[68:69]
	v_pk_add_f32 v[58:59], v[58:59], v[74:75]
	global_store_dwordx4 v[70:71], v[62:65], off sc0 nt
	global_store_dwordx4 v[70:71], v[58:61], off offset:16 sc0 nt
	global_load_dwordx4 v[58:61], v[72:73], off
	v_lshl_add_u64 v[62:63], v[146:147], 0, s[12:13]
	v_lshlrev_b64 v[64:65], 1, v[62:63]
	v_lshl_add_u64 v[66:67], s[78:79], 0, v[64:65]
	v_or_b32_e32 v64, 0x100, v64
	s_waitcnt vmcnt(0)
	v_lshlrev_b32_e32 v72, 16, v58
	v_and_b32_e32 v73, 0xffff0000, v58
	v_lshlrev_b32_e32 v58, 16, v59
	v_and_b32_e32 v59, 0xffff0000, v59
	v_lshlrev_b32_e32 v68, 16, v60
	v_and_b32_e32 v69, 0xffff0000, v60
	v_lshlrev_b32_e32 v60, 16, v61
	v_and_b32_e32 v61, 0xffff0000, v61
	v_pk_add_f32 v[56:57], v[56:57], v[58:59]
	v_pk_add_f32 v[54:55], v[54:55], v[72:73]
	v_pk_add_f32 v[52:53], v[52:53], v[60:61]
	v_pk_add_f32 v[50:51], v[50:51], v[68:69]
	global_store_dwordx4 v[70:71], v[54:57], off offset:512 sc0 nt
	global_store_dwordx4 v[70:71], v[50:53], off offset:528 sc0 nt
	global_load_dwordx4 v[50:53], v[66:67], off
	v_lshl_add_u64 v[54:55], v[62:63], 2, s[70:71]
	v_lshl_add_u64 v[56:57], s[78:79], 0, v[64:65]
	s_waitcnt vmcnt(0)
	v_lshlrev_b32_e32 v60, 16, v50
	v_and_b32_e32 v61, 0xffff0000, v50
	v_lshlrev_b32_e32 v50, 16, v51
	v_and_b32_e32 v51, 0xffff0000, v51
	v_lshlrev_b32_e32 v58, 16, v52
	v_and_b32_e32 v59, 0xffff0000, v52
	v_lshlrev_b32_e32 v52, 16, v53
	v_and_b32_e32 v53, 0xffff0000, v53
	v_pk_add_f32 v[48:49], v[48:49], v[50:51]
	v_pk_add_f32 v[46:47], v[46:47], v[60:61]
	v_pk_add_f32 v[44:45], v[44:45], v[52:53]
	v_pk_add_f32 v[42:43], v[42:43], v[58:59]
	global_store_dwordx4 v[54:55], v[46:49], off sc0 nt
	global_store_dwordx4 v[54:55], v[42:45], off offset:16 sc0 nt
	global_load_dwordx4 v[42:45], v[56:57], off
	v_lshl_add_u64 v[46:47], v[146:147], 0, s[14:15]
	v_lshlrev_b64 v[48:49], 1, v[46:47]
	v_lshl_add_u64 v[50:51], s[78:79], 0, v[48:49]
	v_or_b32_e32 v48, 0x100, v48
	s_waitcnt vmcnt(0)
	v_lshlrev_b32_e32 v56, 16, v42
	v_and_b32_e32 v57, 0xffff0000, v42
	v_lshlrev_b32_e32 v42, 16, v43
	v_and_b32_e32 v43, 0xffff0000, v43
	v_lshlrev_b32_e32 v52, 16, v44
	v_and_b32_e32 v53, 0xffff0000, v44
	v_lshlrev_b32_e32 v44, 16, v45
	v_and_b32_e32 v45, 0xffff0000, v45
	v_pk_add_f32 v[40:41], v[40:41], v[42:43]
	v_pk_add_f32 v[38:39], v[38:39], v[56:57]
	v_pk_add_f32 v[36:37], v[36:37], v[44:45]
	v_pk_add_f32 v[34:35], v[34:35], v[52:53]
	global_store_dwordx4 v[54:55], v[38:41], off offset:512 sc0 nt
	global_store_dwordx4 v[54:55], v[34:37], off offset:528 sc0 nt
	global_load_dwordx4 v[34:37], v[50:51], off
	v_lshl_add_u64 v[38:39], v[46:47], 2, s[70:71]
	v_lshl_add_u64 v[40:41], s[78:79], 0, v[48:49]
	s_waitcnt vmcnt(0)
	v_lshlrev_b32_e32 v44, 16, v34
	v_and_b32_e32 v45, 0xffff0000, v34
	v_lshlrev_b32_e32 v34, 16, v35
	v_and_b32_e32 v35, 0xffff0000, v35
	v_lshlrev_b32_e32 v42, 16, v36
	v_and_b32_e32 v43, 0xffff0000, v36
	v_lshlrev_b32_e32 v36, 16, v37
	v_and_b32_e32 v37, 0xffff0000, v37
	v_pk_add_f32 v[32:33], v[32:33], v[34:35]
	v_pk_add_f32 v[30:31], v[30:31], v[44:45]
	v_pk_add_f32 v[28:29], v[28:29], v[36:37]
	v_pk_add_f32 v[26:27], v[26:27], v[42:43]
	global_store_dwordx4 v[38:39], v[30:33], off sc0 nt
	global_store_dwordx4 v[38:39], v[26:29], off offset:16 sc0 nt
	global_load_dwordx4 v[26:29], v[40:41], off
	v_lshl_add_u64 v[30:31], v[146:147], 0, s[16:17]
	v_lshlrev_b64 v[32:33], 1, v[30:31]
	v_lshl_add_u64 v[34:35], s[78:79], 0, v[32:33]
	v_or_b32_e32 v32, 0x100, v32
	s_waitcnt vmcnt(0)
	v_lshlrev_b32_e32 v40, 16, v26
	v_and_b32_e32 v41, 0xffff0000, v26
	v_lshlrev_b32_e32 v26, 16, v27
	v_and_b32_e32 v27, 0xffff0000, v27
	v_lshlrev_b32_e32 v36, 16, v28
	v_and_b32_e32 v37, 0xffff0000, v28
	v_lshlrev_b32_e32 v28, 16, v29
	v_and_b32_e32 v29, 0xffff0000, v29
	v_pk_add_f32 v[24:25], v[24:25], v[26:27]
	v_pk_add_f32 v[22:23], v[22:23], v[40:41]
	v_pk_add_f32 v[20:21], v[20:21], v[28:29]
	v_pk_add_f32 v[18:19], v[18:19], v[36:37]
	global_store_dwordx4 v[38:39], v[22:25], off offset:512 sc0 nt
	global_store_dwordx4 v[38:39], v[18:21], off offset:528 sc0 nt
	global_load_dwordx4 v[18:21], v[34:35], off
	v_lshl_add_u64 v[22:23], v[30:31], 2, s[70:71]
	v_lshl_add_u64 v[24:25], s[78:79], 0, v[32:33]
	s_waitcnt vmcnt(0)
	v_lshlrev_b32_e32 v28, 16, v18
	v_and_b32_e32 v29, 0xffff0000, v18
	v_lshlrev_b32_e32 v18, 16, v19
	v_and_b32_e32 v19, 0xffff0000, v19
	v_lshlrev_b32_e32 v26, 16, v20
	v_and_b32_e32 v27, 0xffff0000, v20
	v_lshlrev_b32_e32 v20, 16, v21
	v_and_b32_e32 v21, 0xffff0000, v21
	v_pk_add_f32 v[16:17], v[16:17], v[18:19]
	v_pk_add_f32 v[14:15], v[14:15], v[28:29]
	v_pk_add_f32 v[12:13], v[12:13], v[20:21]
	v_pk_add_f32 v[10:11], v[10:11], v[26:27]
	global_store_dwordx4 v[22:23], v[14:17], off sc0 nt
	global_store_dwordx4 v[22:23], v[10:13], off offset:16 sc0 nt
	global_load_dwordx4 v[10:13], v[24:25], off
	s_waitcnt vmcnt(0)
	v_lshlrev_b32_e32 v16, 16, v10
	v_and_b32_e32 v17, 0xffff0000, v10
	v_lshlrev_b32_e32 v10, 16, v11
	v_and_b32_e32 v11, 0xffff0000, v11
	v_lshlrev_b32_e32 v14, 16, v12
	v_and_b32_e32 v15, 0xffff0000, v12
	v_lshlrev_b32_e32 v12, 16, v13
	v_and_b32_e32 v13, 0xffff0000, v13
	v_pk_add_f32 v[8:9], v[8:9], v[10:11]
	v_pk_add_f32 v[6:7], v[6:7], v[16:17]
	v_pk_add_f32 v[4:5], v[4:5], v[12:13]
	v_pk_add_f32 v[2:3], v[2:3], v[14:15]
	global_store_dwordx4 v[22:23], v[6:9], off offset:512 sc0 nt
	global_store_dwordx4 v[22:23], v[2:5], off offset:528 sc0 nt
